# v33 + 4-deep software-pipelined p->bf16 prologue loop with nt loads (gridDim 256 fast path)
# baseline (speedup 1.0000x reference)
; __device__ __forceinline__ unsigned cvt_pk_bf16(float lo, float hi) { unsigned r; asm volatile("v_cvt_pk_bf16_f32 %0, %1, %2" : "=v"(r) : "v"(lo), "v"(hi)); return r; }
; __device__ __forceinline__ void prologue(const Args& A, LAS unsigned char* lds) {
;     ...
;     const float* p = A.in[I_P]; bf16_t* pb = (bf16_t*)(A.ws + WS_PB);
;     const size_t n8 = (size_t)DEPTH * MTOK * PLE / 8, stride = (size_t)gridDim.x * 512;
;     for (size_t i = (size_t)blockIdx.x * 512 + tid; i < n8; i += stride) {
;         const f32x4 a = *(const f32x4*)(p + i * 8), b = *(const f32x4*)(p + i * 8 + 4);
;         u32x4 w; w.x = pg8::cvt_pk_bf16(a[0], a[1]); w.y = pg8::cvt_pk_bf16(a[2], a[3]); w.z = pg8::cvt_pk_bf16(b[0], b[1]); w.w = pg8::cvt_pk_bf16(b[2], b[3]);
;         *(u32x4*)(pb + i * 8) = w;
;     }
.LBB0_206:
	v_writelane_b32 v254, s83, 21
	s_or_b64 exec, exec, s[8:9]
	s_mov_b32 s83, 0
	s_lshl_b64 s[0:1], s[82:83], 9
	v_ashrrev_i32_e32 v67, 31, v66
	s_waitcnt lgkmcnt(0)
	v_lshl_add_u64 v[2:3], s[0:1], 0, v[66:67]
	s_mov_b64 s[0:1], 0x800000
	v_cmp_gt_u64_e32 vcc, s[0:1], v[2:3]
	s_and_saveexec_b64 s[0:1], vcc
	s_cbranch_execz .LBB0_209
	s_mov_b32 s89, s83
	v_readlane_b32 s8, v254, 4
	s_lshl_b64 s[4:5], s[88:89], 9
	s_lshl_b64 s[6:7], s[82:83], 14
	v_readlane_b32 s10, v254, 6
	v_readlane_b32 s11, v254, 7
	s_add_u32 s6, s10, s6
	v_lshlrev_b64 v[4:5], 5, v[66:67]
	v_readlane_b32 s9, v254, 5
	s_addc_u32 s7, s11, s7
	v_lshl_add_u64 v[4:5], s[6:7], 0, v[4:5]
	s_lshl_b64 s[6:7], s[88:89], 14
	s_lshl_b64 s[8:9], s[82:83], 13
	s_add_u32 s8, s80, s8
	s_addc_u32 s9, s81, s9
	v_readlane_b32 s12, v254, 8
	v_readlane_b32 s13, v254, 9
	v_lshl_add_u64 v[6:7], v[66:67], 4, s[8:9]
	s_mov_b64 s[8:9], 0x30000000
	v_lshl_add_u64 v[4:5], v[4:5], 0, 16
	v_lshl_add_u64 v[6:7], v[6:7], 0, s[8:9]
	s_lshl_b64 s[8:9], s[88:89], 13
	s_mov_b64 s[10:11], 0
	s_mov_b64 s[12:13], 0x7fffff
	v_readlane_b32 s14, v254, 10
	v_readlane_b32 s15, v254, 11
	v_readlane_b32 s16, v254, 12
	v_readlane_b32 s17, v254, 13
	v_readlane_b32 s18, v254, 14
	v_readlane_b32 s19, v254, 15
	v_readlane_b32 s20, v254, 16
	v_readlane_b32 s21, v254, 17
	v_readlane_b32 s22, v254, 18
	v_readlane_b32 s23, v254, 19
	s_cmp_lg_u32 s88, 0x100
	s_cbranch_scc1 .LBB0_208
	s_mov_b32 s100, 14
	global_load_dwordx4 v[8:11], v[4:5], off offset:-16 nt
	global_load_dwordx4 v[12:15], v[4:5], off nt
	v_lshl_add_u64 v[4:5], v[4:5], 0, s[6:7]
	global_load_dwordx4 v[16:19], v[4:5], off offset:-16 nt
	global_load_dwordx4 v[20:23], v[4:5], off nt
	v_lshl_add_u64 v[4:5], v[4:5], 0, s[6:7]
	global_load_dwordx4 v[24:27], v[4:5], off offset:-16 nt
	global_load_dwordx4 v[28:31], v[4:5], off nt
	v_lshl_add_u64 v[4:5], v[4:5], 0, s[6:7]
	global_load_dwordx4 v[32:35], v[4:5], off offset:-16 nt
	global_load_dwordx4 v[36:39], v[4:5], off nt
	v_lshl_add_u64 v[4:5], v[4:5], 0, s[6:7]
	s_waitcnt vmcnt(6)
	v_cvt_pk_bf16_f32 v8, v8, v9
	v_cvt_pk_bf16_f32 v9, v10, v11
	v_cvt_pk_bf16_f32 v10, v12, v13
	v_cvt_pk_bf16_f32 v11, v14, v15
	global_store_dwordx4 v[6:7], v[8:11], off
	v_lshl_add_u64 v[6:7], v[6:7], 0, s[8:9]
	s_nop 1
	global_load_dwordx4 v[8:11], v[4:5], off offset:-16 nt
	global_load_dwordx4 v[12:15], v[4:5], off nt
	v_lshl_add_u64 v[4:5], v[4:5], 0, s[6:7]
	s_waitcnt vmcnt(7)
	v_cvt_pk_bf16_f32 v16, v16, v17
	v_cvt_pk_bf16_f32 v17, v18, v19
	v_cvt_pk_bf16_f32 v18, v20, v21
	v_cvt_pk_bf16_f32 v19, v22, v23
	global_store_dwordx4 v[6:7], v[16:19], off
	v_lshl_add_u64 v[6:7], v[6:7], 0, s[8:9]
	s_nop 1
	global_load_dwordx4 v[16:19], v[4:5], off offset:-16 nt
	global_load_dwordx4 v[20:23], v[4:5], off nt
	v_lshl_add_u64 v[4:5], v[4:5], 0, s[6:7]
	s_waitcnt vmcnt(8)
	v_cvt_pk_bf16_f32 v24, v24, v25
	v_cvt_pk_bf16_f32 v25, v26, v27
	v_cvt_pk_bf16_f32 v26, v28, v29
	v_cvt_pk_bf16_f32 v27, v30, v31
	global_store_dwordx4 v[6:7], v[24:27], off
	v_lshl_add_u64 v[6:7], v[6:7], 0, s[8:9]
	s_nop 1
	global_load_dwordx4 v[24:27], v[4:5], off offset:-16 nt
	global_load_dwordx4 v[28:31], v[4:5], off nt
	v_lshl_add_u64 v[4:5], v[4:5], 0, s[6:7]
	s_waitcnt vmcnt(9)
	v_cvt_pk_bf16_f32 v32, v32, v33
	v_cvt_pk_bf16_f32 v33, v34, v35
	v_cvt_pk_bf16_f32 v34, v36, v37
	v_cvt_pk_bf16_f32 v35, v38, v39
	global_store_dwordx4 v[6:7], v[32:35], off
	v_lshl_add_u64 v[6:7], v[6:7], 0, s[8:9]
	s_nop 1
	global_load_dwordx4 v[32:35], v[4:5], off offset:-16 nt
	global_load_dwordx4 v[36:39], v[4:5], off nt
	v_lshl_add_u64 v[4:5], v[4:5], 0, s[6:7]
.Lpconv_loop:
	s_waitcnt vmcnt(9)
	v_cvt_pk_bf16_f32 v8, v8, v9
	v_cvt_pk_bf16_f32 v9, v10, v11
	v_cvt_pk_bf16_f32 v10, v12, v13
	v_cvt_pk_bf16_f32 v11, v14, v15
	global_store_dwordx4 v[6:7], v[8:11], off
	v_lshl_add_u64 v[6:7], v[6:7], 0, s[8:9]
	s_nop 1
	global_load_dwordx4 v[8:11], v[4:5], off offset:-16 nt
	global_load_dwordx4 v[12:15], v[4:5], off nt
	v_lshl_add_u64 v[4:5], v[4:5], 0, s[6:7]
	s_waitcnt vmcnt(9)
	v_cvt_pk_bf16_f32 v16, v16, v17
	v_cvt_pk_bf16_f32 v17, v18, v19
	v_cvt_pk_bf16_f32 v18, v20, v21
	v_cvt_pk_bf16_f32 v19, v22, v23
	global_store_dwordx4 v[6:7], v[16:19], off
	v_lshl_add_u64 v[6:7], v[6:7], 0, s[8:9]
	s_nop 1
	global_load_dwordx4 v[16:19], v[4:5], off offset:-16 nt
	global_load_dwordx4 v[20:23], v[4:5], off nt
	v_lshl_add_u64 v[4:5], v[4:5], 0, s[6:7]
	s_waitcnt vmcnt(9)
	v_cvt_pk_bf16_f32 v24, v24, v25
	v_cvt_pk_bf16_f32 v25, v26, v27
	v_cvt_pk_bf16_f32 v26, v28, v29
	v_cvt_pk_bf16_f32 v27, v30, v31
	global_store_dwordx4 v[6:7], v[24:27], off
	v_lshl_add_u64 v[6:7], v[6:7], 0, s[8:9]
	s_nop 1
	global_load_dwordx4 v[24:27], v[4:5], off offset:-16 nt
	global_load_dwordx4 v[28:31], v[4:5], off nt
	v_lshl_add_u64 v[4:5], v[4:5], 0, s[6:7]
	s_waitcnt vmcnt(9)
	v_cvt_pk_bf16_f32 v32, v32, v33
	v_cvt_pk_bf16_f32 v33, v34, v35
	v_cvt_pk_bf16_f32 v34, v36, v37
	v_cvt_pk_bf16_f32 v35, v38, v39
	global_store_dwordx4 v[6:7], v[32:35], off
	v_lshl_add_u64 v[6:7], v[6:7], 0, s[8:9]
	s_nop 1
	global_load_dwordx4 v[32:35], v[4:5], off offset:-16 nt
	global_load_dwordx4 v[36:39], v[4:5], off nt
	v_lshl_add_u64 v[4:5], v[4:5], 0, s[6:7]
	s_sub_u32 s100, s100, 1
	s_cmp_lg_u32 s100, 0
	s_cbranch_scc1 .Lpconv_loop
	s_waitcnt vmcnt(9)
	v_cvt_pk_bf16_f32 v8, v8, v9
	v_cvt_pk_bf16_f32 v9, v10, v11
	v_cvt_pk_bf16_f32 v10, v12, v13
	v_cvt_pk_bf16_f32 v11, v14, v15
	global_store_dwordx4 v[6:7], v[8:11], off
	v_lshl_add_u64 v[6:7], v[6:7], 0, s[8:9]
	s_waitcnt vmcnt(7)
	v_cvt_pk_bf16_f32 v16, v16, v17
	v_cvt_pk_bf16_f32 v17, v18, v19
	v_cvt_pk_bf16_f32 v18, v20, v21
	v_cvt_pk_bf16_f32 v19, v22, v23
	global_store_dwordx4 v[6:7], v[16:19], off
	v_lshl_add_u64 v[6:7], v[6:7], 0, s[8:9]
	s_waitcnt vmcnt(5)
	v_cvt_pk_bf16_f32 v24, v24, v25
	v_cvt_pk_bf16_f32 v25, v26, v27
	v_cvt_pk_bf16_f32 v26, v28, v29
	v_cvt_pk_bf16_f32 v27, v30, v31
	global_store_dwordx4 v[6:7], v[24:27], off
	v_lshl_add_u64 v[6:7], v[6:7], 0, s[8:9]
	s_waitcnt vmcnt(3)
	v_cvt_pk_bf16_f32 v32, v32, v33
	v_cvt_pk_bf16_f32 v33, v34, v35
	v_cvt_pk_bf16_f32 v34, v36, v37
	v_cvt_pk_bf16_f32 v35, v38, v39
	global_store_dwordx4 v[6:7], v[32:35], off
	v_lshl_add_u64 v[6:7], v[6:7], 0, s[8:9]
	s_branch .LBB0_209
